# selmask cache in selected-branch loop; hand-written GDN scan with 4-set prefetch ring + XCD-colocated v-slices; per-(b,g) tile queues with XCD affinity; exact early-exit in top-k radix select; snake j
# speedup vs baseline: 1.1936x; 1.1936x over previous
.LBB0_29:
	v_readlane_b32 s36, v254, 0
	v_readlane_b32 s37, v254, 1
	s_mov_b64 s[2:3], exec
	v_readlane_b32 s26, v254, 8
	v_readlane_b32 s27, v254, 9
	s_and_b64 s[26:27], s[2:3], s[26:27]
	s_xor_b64 s[38:39], s[26:27], s[2:3]
	s_mov_b64 exec, s[26:27]
	s_load_dwordx2 s[40:41], s[36:37], 0x98
	s_or_saveexec_b64 s[38:39], s[38:39]
	s_waitcnt lgkmcnt(0)
	v_mov_b64_e32 v[16:17], s[40:41]
	s_xor_b64 exec, exec, s[38:39]
	s_cbranch_execz .LBB0_33
	v_mov_b32_e32 v0, v129
	s_load_dwordx2 s[2:3], s[36:37], 0x98
	v_mov_b32_e32 v1, 0x1f510000
	s_waitcnt lgkmcnt(0)
	v_mov_b64_e32 v[16:17], s[2:3]
	global_store_dword v1, v0, s[2:3]
	global_store_dword v1, v0, s[2:3] offset:4
	global_store_dword v1, v0, s[2:3] offset:8
	global_store_dword v1, v0, s[2:3] offset:12

.LBB0_476:
	s_or_b64 exec, exec, s[36:37]
	v_readlane_b32 s36, v254, 0
	v_readlane_b32 s37, v254, 1
	s_waitcnt lgkmcnt(0)
	s_barrier
	s_mov_b64 s[38:39], exec
	v_readlane_b32 s2, v254, 6
	v_readlane_b32 s3, v254, 7
	s_and_b64 s[2:3], s[38:39], s[2:3]
	s_mov_b64 exec, s[2:3]
	s_cbranch_execz .LBB0_478
	v_mov_b32_e32 v0, v129
	s_load_dwordx2 s[2:3], s[36:37], 0x98
	v_mov_b32_e32 v1, 0x1f510000
	s_waitcnt lgkmcnt(0)
	global_store_dword v1, v0, s[2:3]
	global_store_dword v1, v0, s[2:3] offset:4
	global_store_dword v1, v0, s[2:3] offset:8
	global_store_dword v1, v0, s[2:3] offset:12
.LBB0_478:
	s_or_b64 exec, exec, s[38:39]
	v_mov_b32_e32 v0, v218
	s_mov_b32 s94, s82
	s_mov_b32 s32, s82
	s_cmpk_lt_i32 s94, 0x1000
	s_cbranch_scc0 .LBB0_580
	s_load_dwordx2 s[36:37], s[36:37], 0x98
	v_ashrrev_i32_e32 v3, 6, v0
	s_movk_i32 s2, 0x900
	v_and_b32_e32 v4, 15, v0
	v_bfe_u32 v1, v0, 4, 2
	s_waitcnt lgkmcnt(0)
	s_add_u32 s38, s36, 0x1a000000
	s_addc_u32 s39, s37, 0
	s_add_u32 s26, s36, 0x1f000000
	s_addc_u32 s27, s37, 0
	s_add_u32 s28, s36, 0x1f080000
	s_addc_u32 s29, s37, 0
	v_mul_lo_u32 v95, v3, s2
	v_mul_u32_u24_e32 v4, 0x90, v4
	v_and_b32_e32 v5, 48, v0
	s_add_u32 s40, s36, 0x10000020
	v_and_b32_e32 v94, 63, v0
	v_bfe_u32 v97, v0, 2, 2
	v_and_b32_e32 v98, 3, v0
	v_lshlrev_b32_e32 v2, 3, v1
	v_add3_u32 v99, v95, v4, v5
	s_addc_u32 s41, s37, 0
	v_lshlrev_b32_e32 v4, 2, v1
	v_lshlrev_b64 v[0:1], v0, -1
	v_not_b32_e32 v80, v0
	s_add_u32 s78, s36, 0x1f080200
	v_lshlrev_b32_e32 v0, 13, v3
	v_lshlrev_b32_e32 v128, 2, v94
	s_addc_u32 s79, s37, 0
	v_add_u32_e32 v104, 0xa400, v0
	v_or_b32_e32 v0, v0, v128
	s_lshl_b32 s82, s94, 2
	v_lshlrev_b32_e32 v96, 2, v3
	v_not_b32_e32 v81, v1
	v_cmp_eq_u32_e64 s[44:45], 0, v94
	v_add_u32_e32 v105, 0xa400, v0
	v_lshl_add_u64 v[0:1], s[36:37], 0, v[128:129]
	s_mov_b64 s[2:3], 0x1f100000
	s_bitcmp1_b32 s94, 0
	v_cmp_gt_u32_e64 s[42:43], 8, v94
	v_cndmask_b32_e64 v100, 0, 1, s[44:45]
	v_or_b32_e32 v101, 64, v94
	v_or_b32_e32 v102, 0x80, v94
	v_or_b32_e32 v103, 0xc0, v94
	v_cmp_eq_u32_e64 s[46:47], 1, v94
	v_cmp_eq_u32_e64 s[48:49], 2, v94
	v_cmp_eq_u32_e64 s[50:51], 3, v94
	v_cmp_eq_u32_e64 s[52:53], 4, v94
	v_cmp_eq_u32_e64 s[54:55], 5, v94
	v_cmp_eq_u32_e64 s[56:57], 6, v94
	v_cmp_eq_u32_e64 s[58:59], 7, v94
	v_lshl_add_u64 v[82:83], v[0:1], 0, s[2:3]
	v_add_u32_e32 v106, 0x3ff0, v96
	s_cselect_b64 s[80:81], -1, 0
	v_lshlrev_b32_e32 v84, 1, v2
	v_lshlrev_b32_e32 v86, 2, v4
	s_mov_b32 s25, s94
	s_branch .LBB0_481
.LBB0_480:
	v_readlane_b32 s2, v254, 2
	s_nop 0
	s_add_i32 s32, s32, s2
	s_bfe_u32 s3, s32, 0x10009
	s_mul_i32 s3, s3, 0x1ff
	s_xor_b32 s25, s32, s3
	s_mov_b32 s94, s25
	s_lshl_b32 s82, s25, 2
	s_bitcmp1_b32 s25, 0
	s_cselect_b64 s[80:81], -1, 0
	s_cmpk_gt_i32 s32, 0xfff
	s_cbranch_scc1 .LBB0_579

.LBB0_573:
	v_mov_b32_e32 v4, v3
	s_and_saveexec_b64 s[88:89], vcc
	s_cbranch_execz .LBB0_577
	v_add_u32_e32 v10, s84, v105
	ds_read2st64_b32 v[6:7], v10 offset1:1
	ds_read2st64_b32 v[8:9], v10 offset0:16 offset1:17
	s_waitcnt lgkmcnt(0)
	v_add_f32_e32 v4, v6, v8
	v_max_f32_e32 v4, 0, v4
	v_add_u32_e32 v4, 1, v4
	v_cndmask_b32_e64 v5, v4, 0, s[86:87]
	v_add_f32_e32 v4, v7, v9
	ds_read2st64_b32 v[6:7], v10 offset0:2 offset1:3
	ds_read2st64_b32 v[8:9], v10 offset0:18 offset1:19
	v_max_f32_e32 v4, 0, v4
	v_add_u32_e32 v4, 1, v4
	v_cndmask_b32_e64 v4, v4, 0, s[60:61]
	v_cmp_lt_u32_e64 s[66:67], s16, v5
	s_waitcnt lgkmcnt(0)
	v_add_f32_e32 v6, v6, v8
	v_max_f32_e32 v6, 0, v6
	v_add_f32_e32 v7, v7, v9
	v_add_u32_e32 v6, 1, v6
	v_max_f32_e32 v7, 0, v7
	v_cndmask_b32_e64 v6, v6, 0, s[62:63]
	v_add_u32_e32 v7, 1, v7
	s_bcnt1_i32_b64 s2, s[66:67]
	v_cmp_lt_u32_e64 s[66:67], s16, v4
	v_cndmask_b32_e64 v7, v7, 0, s[64:65]
	s_bcnt1_i32_b64 s3, s[66:67]
	v_cmp_lt_u32_e64 s[66:67], s16, v6
	s_add_i32 s2, s3, s2
	s_bcnt1_i32_b64 s3, s[66:67]
	v_cmp_lt_u32_e64 s[66:67], s16, v7
	s_add_i32 s2, s2, s3
	s_bcnt1_i32_b64 s3, s[66:67]
	s_add_i32 s2, s2, s3
	s_cmp_gt_u32 s2, 12
	s_cselect_b32 s2, 2.0, 0
	s_or_b32 s3, s2, 0x20000000
	v_cmp_le_u32_e64 s[66:67], s3, v5
	s_bcnt1_i32_b64 s68, s[66:67]
	v_cmp_le_u32_e64 s[66:67], s3, v4
	s_bcnt1_i32_b64 s66, s[66:67]
	s_add_i32 s68, s66, s68
	v_cmp_le_u32_e64 s[66:67], s3, v6
	s_bcnt1_i32_b64 s66, s[66:67]
	s_add_i32 s68, s68, s66
	v_cmp_le_u32_e64 s[66:67], s3, v7
	s_bcnt1_i32_b64 s66, s[66:67]
	s_add_i32 s68, s68, s66
	s_cmp_gt_u32 s68, 12
	s_cselect_b32 s2, s3, s2
	s_cmp_eq_u32 s68, 13
	s_cbranch_scc1 .Ltopk_early
	s_or_b32 s3, s2, 0x10000000
	v_cmp_le_u32_e64 s[66:67], s3, v5
	s_bcnt1_i32_b64 s68, s[66:67]
	v_cmp_le_u32_e64 s[66:67], s3, v4
	s_bcnt1_i32_b64 s66, s[66:67]
	s_add_i32 s68, s66, s68
	v_cmp_le_u32_e64 s[66:67], s3, v6
	s_bcnt1_i32_b64 s66, s[66:67]
	s_add_i32 s68, s68, s66
	v_cmp_le_u32_e64 s[66:67], s3, v7
	s_bcnt1_i32_b64 s66, s[66:67]
	s_add_i32 s68, s68, s66
	s_cmp_gt_u32 s68, 12
	s_cselect_b32 s2, s3, s2
	s_cmp_eq_u32 s68, 13
	s_cbranch_scc1 .Ltopk_early
	s_or_b32 s3, s2, 0x8000000
	v_cmp_le_u32_e64 s[66:67], s3, v5
	s_bcnt1_i32_b64 s68, s[66:67]
	v_cmp_le_u32_e64 s[66:67], s3, v4
	s_bcnt1_i32_b64 s66, s[66:67]
	s_add_i32 s68, s66, s68
	v_cmp_le_u32_e64 s[66:67], s3, v6
	s_bcnt1_i32_b64 s66, s[66:67]
	s_add_i32 s68, s68, s66
	v_cmp_le_u32_e64 s[66:67], s3, v7
	s_bcnt1_i32_b64 s66, s[66:67]
	s_add_i32 s68, s68, s66
	s_cmp_gt_u32 s68, 12
	s_cselect_b32 s2, s3, s2
	s_cmp_eq_u32 s68, 13
	s_cbranch_scc1 .Ltopk_early
	s_or_b32 s3, s2, 0x4000000
	v_cmp_le_u32_e64 s[66:67], s3, v5
	s_bcnt1_i32_b64 s68, s[66:67]
	v_cmp_le_u32_e64 s[66:67], s3, v4
	s_bcnt1_i32_b64 s66, s[66:67]
	s_add_i32 s68, s66, s68
	v_cmp_le_u32_e64 s[66:67], s3, v6
	s_bcnt1_i32_b64 s66, s[66:67]
	s_add_i32 s68, s68, s66
	v_cmp_le_u32_e64 s[66:67], s3, v7
	s_bcnt1_i32_b64 s66, s[66:67]
	s_add_i32 s68, s68, s66
	s_cmp_gt_u32 s68, 12
	s_cselect_b32 s2, s3, s2
	s_cmp_eq_u32 s68, 13
	s_cbranch_scc1 .Ltopk_early
	s_or_b32 s3, s2, 0x2000000
	v_cmp_le_u32_e64 s[66:67], s3, v5
	s_bcnt1_i32_b64 s68, s[66:67]
	v_cmp_le_u32_e64 s[66:67], s3, v4
	s_bcnt1_i32_b64 s66, s[66:67]
	s_add_i32 s68, s66, s68
	v_cmp_le_u32_e64 s[66:67], s3, v6
	s_bcnt1_i32_b64 s66, s[66:67]
	s_add_i32 s68, s68, s66
	v_cmp_le_u32_e64 s[66:67], s3, v7
	s_bcnt1_i32_b64 s66, s[66:67]
	s_add_i32 s68, s68, s66
	s_cmp_gt_u32 s68, 12
	s_cselect_b32 s2, s3, s2
	s_cmp_eq_u32 s68, 13
	s_cbranch_scc1 .Ltopk_early
	s_or_b32 s3, s2, 0x1000000
	v_cmp_le_u32_e64 s[66:67], s3, v5
	s_bcnt1_i32_b64 s68, s[66:67]
	v_cmp_le_u32_e64 s[66:67], s3, v4
	s_bcnt1_i32_b64 s66, s[66:67]
	s_add_i32 s68, s66, s68
	v_cmp_le_u32_e64 s[66:67], s3, v6
	s_bcnt1_i32_b64 s66, s[66:67]
	s_add_i32 s68, s68, s66
	v_cmp_le_u32_e64 s[66:67], s3, v7
	s_bcnt1_i32_b64 s66, s[66:67]
	s_add_i32 s68, s68, s66
	s_cmp_gt_u32 s68, 12
	s_cselect_b32 s2, s3, s2
	s_cmp_eq_u32 s68, 13
	s_cbranch_scc1 .Ltopk_early
	s_or_b32 s3, s2, 0x800000
	v_cmp_le_u32_e64 s[66:67], s3, v5
	s_bcnt1_i32_b64 s68, s[66:67]
	v_cmp_le_u32_e64 s[66:67], s3, v4
	s_bcnt1_i32_b64 s66, s[66:67]
	s_add_i32 s68, s66, s68
	v_cmp_le_u32_e64 s[66:67], s3, v6
	s_bcnt1_i32_b64 s66, s[66:67]
	s_add_i32 s68, s68, s66
	v_cmp_le_u32_e64 s[66:67], s3, v7
	s_bcnt1_i32_b64 s66, s[66:67]
	s_add_i32 s68, s68, s66
	s_cmp_gt_u32 s68, 12
	s_cselect_b32 s2, s3, s2
	s_cmp_eq_u32 s68, 13
	s_cbranch_scc1 .Ltopk_early
	s_or_b32 s3, s2, 0x400000
	v_cmp_le_u32_e64 s[66:67], s3, v5
	s_bcnt1_i32_b64 s68, s[66:67]
	v_cmp_le_u32_e64 s[66:67], s3, v4
	s_bcnt1_i32_b64 s66, s[66:67]
	s_add_i32 s68, s66, s68
	v_cmp_le_u32_e64 s[66:67], s3, v6
	s_bcnt1_i32_b64 s66, s[66:67]
	s_add_i32 s68, s68, s66
	v_cmp_le_u32_e64 s[66:67], s3, v7
	s_bcnt1_i32_b64 s66, s[66:67]
	s_add_i32 s68, s68, s66
	s_cmp_gt_u32 s68, 12
	s_cselect_b32 s2, s3, s2
	s_cmp_eq_u32 s68, 13
	s_cbranch_scc1 .Ltopk_early
	s_or_b32 s3, s2, 0x200000
	v_cmp_le_u32_e64 s[66:67], s3, v5
	s_bcnt1_i32_b64 s68, s[66:67]
	v_cmp_le_u32_e64 s[66:67], s3, v4
	s_bcnt1_i32_b64 s66, s[66:67]
	s_add_i32 s68, s66, s68
	v_cmp_le_u32_e64 s[66:67], s3, v6
	s_bcnt1_i32_b64 s66, s[66:67]
	s_add_i32 s68, s68, s66
	v_cmp_le_u32_e64 s[66:67], s3, v7
	s_bcnt1_i32_b64 s66, s[66:67]
	s_add_i32 s68, s68, s66
	s_cmp_gt_u32 s68, 12
	s_cselect_b32 s2, s3, s2
	s_cmp_eq_u32 s68, 13
	s_cbranch_scc1 .Ltopk_early
	s_or_b32 s3, s2, 0x100000
	v_cmp_le_u32_e64 s[66:67], s3, v5
	s_bcnt1_i32_b64 s68, s[66:67]
	v_cmp_le_u32_e64 s[66:67], s3, v4
	s_bcnt1_i32_b64 s66, s[66:67]
	s_add_i32 s68, s66, s68
	v_cmp_le_u32_e64 s[66:67], s3, v6
	s_bcnt1_i32_b64 s66, s[66:67]
	s_add_i32 s68, s68, s66
	v_cmp_le_u32_e64 s[66:67], s3, v7
	s_bcnt1_i32_b64 s66, s[66:67]
	s_add_i32 s68, s68, s66
	s_cmp_gt_u32 s68, 12
	s_cselect_b32 s2, s3, s2
	s_cmp_eq_u32 s68, 13
	s_cbranch_scc1 .Ltopk_early
	s_or_b32 s3, s2, 0x80000
	v_cmp_le_u32_e64 s[66:67], s3, v5
	s_bcnt1_i32_b64 s68, s[66:67]
	v_cmp_le_u32_e64 s[66:67], s3, v4
	s_bcnt1_i32_b64 s66, s[66:67]
	s_add_i32 s68, s66, s68
	v_cmp_le_u32_e64 s[66:67], s3, v6
	s_bcnt1_i32_b64 s66, s[66:67]
	s_add_i32 s68, s68, s66
	v_cmp_le_u32_e64 s[66:67], s3, v7
	s_bcnt1_i32_b64 s66, s[66:67]
	s_add_i32 s68, s68, s66
	s_cmp_gt_u32 s68, 12
	s_cselect_b32 s2, s3, s2
	s_cmp_eq_u32 s68, 13
	s_cbranch_scc1 .Ltopk_early
	s_or_b32 s3, s2, 0x40000
	v_cmp_le_u32_e64 s[66:67], s3, v5
	s_bcnt1_i32_b64 s68, s[66:67]
	v_cmp_le_u32_e64 s[66:67], s3, v4
	s_bcnt1_i32_b64 s66, s[66:67]
	s_add_i32 s68, s66, s68
	v_cmp_le_u32_e64 s[66:67], s3, v6
	s_bcnt1_i32_b64 s66, s[66:67]
	s_add_i32 s68, s68, s66
	v_cmp_le_u32_e64 s[66:67], s3, v7
	s_bcnt1_i32_b64 s66, s[66:67]
	s_add_i32 s68, s68, s66
	s_cmp_gt_u32 s68, 12
	s_cselect_b32 s2, s3, s2
	s_cmp_eq_u32 s68, 13
	s_cbranch_scc1 .Ltopk_early
	s_or_b32 s3, s2, 0x20000
	v_cmp_le_u32_e64 s[66:67], s3, v5
	s_bcnt1_i32_b64 s68, s[66:67]
	v_cmp_le_u32_e64 s[66:67], s3, v4
	s_bcnt1_i32_b64 s66, s[66:67]
	s_add_i32 s68, s66, s68
	v_cmp_le_u32_e64 s[66:67], s3, v6
	s_bcnt1_i32_b64 s66, s[66:67]
	s_add_i32 s68, s68, s66
	v_cmp_le_u32_e64 s[66:67], s3, v7
	s_bcnt1_i32_b64 s66, s[66:67]
	s_add_i32 s68, s68, s66
	s_cmp_gt_u32 s68, 12
	s_cselect_b32 s2, s3, s2
	s_cmp_eq_u32 s68, 13
	s_cbranch_scc1 .Ltopk_early
	s_or_b32 s3, s2, 0x10000
	v_cmp_le_u32_e64 s[66:67], s3, v5
	s_bcnt1_i32_b64 s68, s[66:67]
	v_cmp_le_u32_e64 s[66:67], s3, v4
	s_bcnt1_i32_b64 s66, s[66:67]
	s_add_i32 s68, s66, s68
	v_cmp_le_u32_e64 s[66:67], s3, v6
	s_bcnt1_i32_b64 s66, s[66:67]
	s_add_i32 s68, s68, s66
	v_cmp_le_u32_e64 s[66:67], s3, v7
	s_bcnt1_i32_b64 s66, s[66:67]
	s_add_i32 s68, s68, s66
	s_cmp_gt_u32 s68, 12
	s_cselect_b32 s2, s3, s2
	s_cmp_eq_u32 s68, 13
	s_cbranch_scc1 .Ltopk_early
	s_or_b32 s3, s2, 0x8000
	v_cmp_le_u32_e64 s[66:67], s3, v5
	s_bcnt1_i32_b64 s68, s[66:67]
	v_cmp_le_u32_e64 s[66:67], s3, v4
	s_bcnt1_i32_b64 s66, s[66:67]
	s_add_i32 s68, s66, s68
	v_cmp_le_u32_e64 s[66:67], s3, v6
	s_bcnt1_i32_b64 s66, s[66:67]
	s_add_i32 s68, s68, s66
	v_cmp_le_u32_e64 s[66:67], s3, v7
	s_bcnt1_i32_b64 s66, s[66:67]
	s_add_i32 s68, s68, s66
	s_cmp_gt_u32 s68, 12
	s_cselect_b32 s2, s3, s2
	s_cmp_eq_u32 s68, 13
	s_cbranch_scc1 .Ltopk_early
	s_or_b32 s3, s2, 0x4000
	v_cmp_le_u32_e64 s[66:67], s3, v5
	s_bcnt1_i32_b64 s68, s[66:67]
	v_cmp_le_u32_e64 s[66:67], s3, v4
	s_bcnt1_i32_b64 s66, s[66:67]
	s_add_i32 s68, s66, s68
	v_cmp_le_u32_e64 s[66:67], s3, v6
	s_bcnt1_i32_b64 s66, s[66:67]
	s_add_i32 s68, s68, s66
	v_cmp_le_u32_e64 s[66:67], s3, v7
	s_bcnt1_i32_b64 s66, s[66:67]
	s_add_i32 s68, s68, s66
	s_cmp_gt_u32 s68, 12
	s_cselect_b32 s2, s3, s2
	s_cmp_eq_u32 s68, 13
	s_cbranch_scc1 .Ltopk_early
	s_or_b32 s3, s2, 0x2000
	v_cmp_le_u32_e64 s[66:67], s3, v5
	s_bcnt1_i32_b64 s68, s[66:67]
	v_cmp_le_u32_e64 s[66:67], s3, v4
	s_bcnt1_i32_b64 s66, s[66:67]
	s_add_i32 s68, s66, s68
	v_cmp_le_u32_e64 s[66:67], s3, v6
	s_bcnt1_i32_b64 s66, s[66:67]
	s_add_i32 s68, s68, s66
	v_cmp_le_u32_e64 s[66:67], s3, v7
	s_bcnt1_i32_b64 s66, s[66:67]
	s_add_i32 s68, s68, s66
	s_cmp_gt_u32 s68, 12
	s_cselect_b32 s2, s3, s2
	s_cmp_eq_u32 s68, 13
	s_cbranch_scc1 .Ltopk_early
	s_or_b32 s3, s2, 0x1000
	v_cmp_le_u32_e64 s[66:67], s3, v5
	s_bcnt1_i32_b64 s68, s[66:67]
	v_cmp_le_u32_e64 s[66:67], s3, v4
	s_bcnt1_i32_b64 s66, s[66:67]
	s_add_i32 s68, s66, s68
	v_cmp_le_u32_e64 s[66:67], s3, v6
	s_bcnt1_i32_b64 s66, s[66:67]
	s_add_i32 s68, s68, s66
	v_cmp_le_u32_e64 s[66:67], s3, v7
	s_bcnt1_i32_b64 s66, s[66:67]
	s_add_i32 s68, s68, s66
	s_cmp_gt_u32 s68, 12
	s_cselect_b32 s2, s3, s2
	s_cmp_eq_u32 s68, 13
	s_cbranch_scc1 .Ltopk_early
	s_or_b32 s3, s2, 0x800
	v_cmp_le_u32_e64 s[66:67], s3, v5
	s_bcnt1_i32_b64 s68, s[66:67]
	v_cmp_le_u32_e64 s[66:67], s3, v4
	s_bcnt1_i32_b64 s66, s[66:67]
	s_add_i32 s68, s66, s68
	v_cmp_le_u32_e64 s[66:67], s3, v6
	s_bcnt1_i32_b64 s66, s[66:67]
	s_add_i32 s68, s68, s66
	v_cmp_le_u32_e64 s[66:67], s3, v7
	s_bcnt1_i32_b64 s66, s[66:67]
	s_add_i32 s68, s68, s66
	s_cmp_gt_u32 s68, 12
	s_cselect_b32 s2, s3, s2
	s_cmp_eq_u32 s68, 13
	s_cbranch_scc1 .Ltopk_early
	s_or_b32 s3, s2, 0x400
	v_cmp_le_u32_e64 s[66:67], s3, v5
	s_bcnt1_i32_b64 s68, s[66:67]
	v_cmp_le_u32_e64 s[66:67], s3, v4
	s_bcnt1_i32_b64 s66, s[66:67]
	s_add_i32 s68, s66, s68
	v_cmp_le_u32_e64 s[66:67], s3, v6
	s_bcnt1_i32_b64 s66, s[66:67]
	s_add_i32 s68, s68, s66
	v_cmp_le_u32_e64 s[66:67], s3, v7
	s_bcnt1_i32_b64 s66, s[66:67]
	s_add_i32 s68, s68, s66
	s_cmp_gt_u32 s68, 12
	s_cselect_b32 s2, s3, s2
	s_cmp_eq_u32 s68, 13
	s_cbranch_scc1 .Ltopk_early
	s_or_b32 s3, s2, 0x200
	v_cmp_le_u32_e64 s[66:67], s3, v5
	s_bcnt1_i32_b64 s68, s[66:67]
	v_cmp_le_u32_e64 s[66:67], s3, v4
	s_bcnt1_i32_b64 s66, s[66:67]
	s_add_i32 s68, s66, s68
	v_cmp_le_u32_e64 s[66:67], s3, v6
	s_bcnt1_i32_b64 s66, s[66:67]
	s_add_i32 s68, s68, s66
	v_cmp_le_u32_e64 s[66:67], s3, v7
	s_bcnt1_i32_b64 s66, s[66:67]
	s_add_i32 s68, s68, s66
	s_cmp_gt_u32 s68, 12
	s_cselect_b32 s2, s3, s2
	s_cmp_eq_u32 s68, 13
	s_cbranch_scc1 .Ltopk_early
	s_or_b32 s3, s2, 0x100
	v_cmp_le_u32_e64 s[66:67], s3, v5
	s_bcnt1_i32_b64 s68, s[66:67]
	v_cmp_le_u32_e64 s[66:67], s3, v4
	s_bcnt1_i32_b64 s66, s[66:67]
	s_add_i32 s68, s66, s68
	v_cmp_le_u32_e64 s[66:67], s3, v6
	s_bcnt1_i32_b64 s66, s[66:67]
	s_add_i32 s68, s68, s66
	v_cmp_le_u32_e64 s[66:67], s3, v7
	s_bcnt1_i32_b64 s66, s[66:67]
	s_add_i32 s68, s68, s66
	s_cmp_gt_u32 s68, 12
	s_cselect_b32 s2, s3, s2
	s_cmp_eq_u32 s68, 13
	s_cbranch_scc1 .Ltopk_early
	s_or_b32 s3, s2, 0x80
	v_cmp_le_u32_e64 s[66:67], s3, v5
	s_bcnt1_i32_b64 s68, s[66:67]
	v_cmp_le_u32_e64 s[66:67], s3, v4
	s_bcnt1_i32_b64 s66, s[66:67]
	s_add_i32 s68, s66, s68
	v_cmp_le_u32_e64 s[66:67], s3, v6
	s_bcnt1_i32_b64 s66, s[66:67]
	s_add_i32 s68, s68, s66
	v_cmp_le_u32_e64 s[66:67], s3, v7
	s_bcnt1_i32_b64 s66, s[66:67]
	s_add_i32 s68, s68, s66
	s_cmp_gt_u32 s68, 12
	s_cselect_b32 s2, s3, s2
	s_cmp_eq_u32 s68, 13
	s_cbranch_scc1 .Ltopk_early
	s_or_b32 s3, s2, 64
	v_cmp_le_u32_e64 s[66:67], s3, v5
	s_bcnt1_i32_b64 s68, s[66:67]
	v_cmp_le_u32_e64 s[66:67], s3, v4
	s_bcnt1_i32_b64 s66, s[66:67]
	s_add_i32 s68, s66, s68
	v_cmp_le_u32_e64 s[66:67], s3, v6
	s_bcnt1_i32_b64 s66, s[66:67]
	s_add_i32 s68, s68, s66
	v_cmp_le_u32_e64 s[66:67], s3, v7
	s_bcnt1_i32_b64 s66, s[66:67]
	s_add_i32 s68, s68, s66
	s_cmp_gt_u32 s68, 12
	s_cselect_b32 s2, s3, s2
	s_cmp_eq_u32 s68, 13
	s_cbranch_scc1 .Ltopk_early
	s_or_b32 s3, s2, 32
	v_cmp_le_u32_e64 s[66:67], s3, v5
	s_bcnt1_i32_b64 s68, s[66:67]
	v_cmp_le_u32_e64 s[66:67], s3, v4
	s_bcnt1_i32_b64 s66, s[66:67]
	s_add_i32 s68, s66, s68
	v_cmp_le_u32_e64 s[66:67], s3, v6
	s_bcnt1_i32_b64 s66, s[66:67]
	s_add_i32 s68, s68, s66
	v_cmp_le_u32_e64 s[66:67], s3, v7
	s_bcnt1_i32_b64 s66, s[66:67]
	s_add_i32 s68, s68, s66
	s_cmp_gt_u32 s68, 12
	s_cselect_b32 s2, s3, s2
	s_cmp_eq_u32 s68, 13
	s_cbranch_scc1 .Ltopk_early
	s_or_b32 s3, s2, 16
	v_cmp_le_u32_e64 s[66:67], s3, v5
	s_bcnt1_i32_b64 s68, s[66:67]
	v_cmp_le_u32_e64 s[66:67], s3, v4
	s_bcnt1_i32_b64 s66, s[66:67]
	s_add_i32 s68, s66, s68
	v_cmp_le_u32_e64 s[66:67], s3, v6
	s_bcnt1_i32_b64 s66, s[66:67]
	s_add_i32 s68, s68, s66
	v_cmp_le_u32_e64 s[66:67], s3, v7
	s_bcnt1_i32_b64 s66, s[66:67]
	s_add_i32 s68, s68, s66
	s_cmp_gt_u32 s68, 12
	s_cselect_b32 s2, s3, s2
	s_cmp_eq_u32 s68, 13
	s_cbranch_scc1 .Ltopk_early
	s_or_b32 s3, s2, 8
	v_cmp_le_u32_e64 s[66:67], s3, v5
	s_bcnt1_i32_b64 s68, s[66:67]
	v_cmp_le_u32_e64 s[66:67], s3, v4
	s_bcnt1_i32_b64 s66, s[66:67]
	s_add_i32 s68, s66, s68
	v_cmp_le_u32_e64 s[66:67], s3, v6
	s_bcnt1_i32_b64 s66, s[66:67]
	s_add_i32 s68, s68, s66
	v_cmp_le_u32_e64 s[66:67], s3, v7
	s_bcnt1_i32_b64 s66, s[66:67]
	s_add_i32 s68, s68, s66
	s_cmp_gt_u32 s68, 12
	s_cselect_b32 s2, s3, s2
	s_cmp_eq_u32 s68, 13
	s_cbranch_scc1 .Ltopk_early
	s_or_b32 s3, s2, 4
	v_cmp_le_u32_e64 s[66:67], s3, v5
	s_bcnt1_i32_b64 s68, s[66:67]
	v_cmp_le_u32_e64 s[66:67], s3, v4
	s_bcnt1_i32_b64 s66, s[66:67]
	s_add_i32 s68, s66, s68
	v_cmp_le_u32_e64 s[66:67], s3, v6
	s_bcnt1_i32_b64 s66, s[66:67]
	s_add_i32 s68, s68, s66
	v_cmp_le_u32_e64 s[66:67], s3, v7
	s_bcnt1_i32_b64 s66, s[66:67]
	s_add_i32 s68, s68, s66
	s_cmp_gt_u32 s68, 12
	s_cselect_b32 s2, s3, s2
	s_cmp_eq_u32 s68, 13
	s_cbranch_scc1 .Ltopk_early
	s_or_b32 s3, s2, 2
	v_cmp_le_u32_e64 s[66:67], s3, v5
	s_bcnt1_i32_b64 s68, s[66:67]
	v_cmp_le_u32_e64 s[66:67], s3, v4
	s_bcnt1_i32_b64 s66, s[66:67]
	s_add_i32 s68, s66, s68
	v_cmp_le_u32_e64 s[66:67], s3, v6
	s_bcnt1_i32_b64 s66, s[66:67]
	s_add_i32 s68, s68, s66
	v_cmp_le_u32_e64 s[66:67], s3, v7
	s_bcnt1_i32_b64 s66, s[66:67]
	s_add_i32 s68, s68, s66
	s_cmp_gt_u32 s68, 12
	s_cselect_b32 s2, s3, s2
	s_cmp_eq_u32 s68, 13
	s_cbranch_scc1 .Ltopk_early
	s_or_b32 s3, s2, 1
	v_cmp_le_u32_e64 s[66:67], s3, v5
	s_bcnt1_i32_b64 s68, s[66:67]
	v_cmp_le_u32_e64 s[66:67], s3, v4
	s_bcnt1_i32_b64 s66, s[66:67]
	s_add_i32 s68, s66, s68
	v_cmp_le_u32_e64 s[66:67], s3, v6
	s_bcnt1_i32_b64 s66, s[66:67]
	s_add_i32 s68, s68, s66
	v_cmp_le_u32_e64 s[66:67], s3, v7
	s_bcnt1_i32_b64 s66, s[66:67]
	s_add_i32 s68, s68, s66
	s_cmp_gt_u32 s68, 12
	s_cselect_b32 s2, s3, s2
.Ltopk_early:
	s_mov_b32 s90, s2
	v_cmp_lt_u32_e64 s[66:67], s90, v5
	v_cmp_lt_u32_e64 s[68:69], s90, v4
	s_bcnt1_i32_b64 s2, s[66:67]
	s_bcnt1_i32_b64 s3, s[68:69]
	v_cmp_lt_u32_e64 s[70:71], s90, v6
	s_bcnt1_i32_b64 s74, s[70:71]
	v_cmp_lt_u32_e64 s[72:73], s90, v7
	s_add_i32 s2, s2, s3
	s_bcnt1_i32_b64 s72, s[72:73]
	s_add_i32 s2, s2, s74
	s_add_i32 s2, s2, s72
	v_cmp_eq_u32_e64 s[72:73], s90, v5
	s_sub_i32 s91, 13, s2
	v_cmp_ge_u32_e64 s[76:77], s90, v7
	v_and_b32_e32 v8, s72, v80
	v_and_b32_e32 v5, s73, v81
	v_bcnt_u32_b32 v8, v8, 0
	v_bcnt_u32_b32 v5, v5, v8
	v_cmp_gt_i32_e64 s[74:75], s91, v5
	s_and_b64 s[2:3], s[72:73], s[74:75]
	s_or_b64 s[2:3], s[66:67], s[2:3]
	s_bcnt1_i32_b64 s66, s[72:73]
	s_sub_i32 s67, s91, s66
	s_cmp_gt_i32 s91, s66
	v_cndmask_b32_e64 v5, 0, 1, s[2:3]
	v_cmp_eq_u32_e64 s[72:73], s90, v4
	s_cselect_b32 s91, s67, 0
	v_cmp_ne_u32_e64 s[66:67], 0, v5
	v_and_b32_e32 v5, s72, v80
	v_and_b32_e32 v4, s73, v81
	v_bcnt_u32_b32 v5, v5, 0
	v_bcnt_u32_b32 v4, v4, v5
	v_cmp_gt_i32_e64 s[74:75], s91, v4
	s_and_b64 s[2:3], s[72:73], s[74:75]
	s_or_b64 s[68:69], s[68:69], s[2:3]
	s_bcnt1_i32_b64 s2, s[72:73]
	v_cmp_eq_u32_e64 s[72:73], s90, v6
	s_sub_i32 s3, s91, s2
	v_cndmask_b32_e64 v4, 0, 1, s[68:69]
	v_and_b32_e32 v5, s72, v80
	s_cmp_gt_i32 s91, s2
	v_cmp_ne_u32_e64 s[68:69], 0, v4
	v_and_b32_e32 v4, s73, v81
	v_bcnt_u32_b32 v5, v5, 0
	s_cselect_b32 s2, s3, 0
	v_bcnt_u32_b32 v4, v4, v5
	v_cmp_gt_i32_e64 s[74:75], s2, v4
	s_and_b64 s[74:75], s[72:73], s[74:75]
	s_or_b64 s[70:71], s[70:71], s[74:75]
	v_cndmask_b32_e64 v4, 0, 1, s[70:71]
	v_cmp_ne_u32_e64 s[70:71], 0, v4
	v_cmp_eq_u32_e64 s[74:75], s90, v7
	s_mov_b64 s[90:91], -1
	s_and_saveexec_b64 s[92:93], s[76:77]
	s_cbranch_execz .LBB0_576
	s_bcnt1_i32_b64 s3, s[72:73]
	v_and_b32_e32 v5, s74, v80
	s_cmp_gt_i32 s2, s3
	v_and_b32_e32 v4, s75, v81
	v_bcnt_u32_b32 v5, v5, 0
	s_cselect_b64 s[76:77], -1, 0
	s_sub_i32 s2, s2, s3
	v_bcnt_u32_b32 v4, v4, v5
	v_cmp_gt_i32_e64 s[72:73], s2, v4
	s_and_b64 s[2:3], s[74:75], s[76:77]
	s_and_b64 s[2:3], s[2:3], s[72:73]
	s_orn2_b64 s[90:91], s[2:3], exec

.LBB0_633:
	s_or_b64 exec, exec, s[36:37]
	v_readlane_b32 s36, v254, 0
	v_readlane_b32 s37, v254, 1
	s_mov_b32 s2, s82
	s_waitcnt lgkmcnt(0)
	s_barrier
	s_cmp_gt_i32 s2, 31
	s_cbranch_scc1 .LBB0_637
	s_setprio 3
	s_load_dwordx2 s[38:39], s[36:37], 0x98
	v_and_b32_e32 v100, 63, v218
	v_lshrrev_b32_e32 v101, 6, v218
	v_and_b32_e32 v102, 15, v100
	v_lshrrev_b32_e32 v103, 4, v100
	v_mul_u32_u24_e32 v104, 0x90, v102
	v_lshl_add_u32 v105, v103, 3, v104
	v_lshl_add_u32 v191, v101, 5, v105
	v_lshl_add_u32 v192, v103, 4, v104
	s_lshr_b32 s2, s82, 3
	s_lshl_b32 s3, s2, 12
	v_lshlrev_b32_e32 v105, 8, v102
	v_lshl_add_u32 v105, v101, 6, v105
	v_lshl_add_u32 v105, v103, 4, v105
	v_add_u32_e32 v186, s3, v105
	v_lshlrev_b32_e32 v105, 7, v102
	v_lshl_add_u32 v105, v101, 11, v105
	v_lshl_add_u32 v105, v103, 4, v105
	v_add_u32_e32 v187, 0x4000, v105
	v_add_u32_e32 v188, 0x6000, v105
	v_add_u32_e32 v189, 0x8000, v105
	v_add_u32_e32 v190, 0xa000, v105
	v_lshlrev_b32_e32 v105, 2, v102
	v_lshl_add_u32 v105, v103, 12, v105
	v_lshl_add_u32 v193, v101, 14, v105
	s_and_b32 s25, s82, 7
	s_lshr_b32 s26, s25, 2
	s_and_b32 s27, s25, 3
	s_waitcnt lgkmcnt(0)
	s_mul_i32 s28, s25, 0xc00000
	s_add_u32 s28, s28, 0x12000000
	s_add_u32 s40, s38, s28
	s_addc_u32 s41, s39, 0
	s_lshl_b32 s28, s25, 10
	s_add_u32 s28, s28, 0x1f500000
	s_add_u32 s42, s38, s28
	s_addc_u32 s43, s39, 0
	s_lshl_b32 s28, s26, 24
	s_lshl_b32 s29, s27, 8
	s_add_u32 s28, s28, s29
	s_lshl_b32 s29, s2, 6
	s_add_u32 s28, s28, s29
	s_add_u32 s28, s28, 0x18000000
	s_add_u32 s44, s38, s28
	s_addc_u32 s45, s39, 0
	s_mov_b32 s46, 0
	v_mov_b32_e32 v168, 0
	v_mov_b32_e32 v169, 0
	v_mov_b32_e32 v170, 0
	v_mov_b32_e32 v171, 0
	v_mov_b32_e32 v184, 0
	v_mov_b32_e32 v185, 0
	ds_write_b64 v191, v[184:185]
	global_load_dwordx4 v[0:3], v186, s[40:41]
	global_load_dwordx4 v[4:7], v187, s[40:41]
	global_load_dwordx4 v[8:11], v187, s[40:41] offset:64
	global_load_dwordx4 v[20:23], v189, s[40:41]
	global_load_dwordx4 v[24:27], v189, s[40:41] offset:64
	global_load_dwordx4 v[12:15], v188, s[40:41]
	global_load_dwordx4 v[16:19], v188, s[40:41] offset:64
	global_load_dwordx4 v[28:31], v190, s[40:41]
	global_load_dwordx4 v[32:35], v190, s[40:41] offset:64
	global_load_dword v36, v129, s[42:43]
	s_cmp_lt_u32 s46, 0xff
	s_cselect_b32 s2, 0xc000, 0
	s_cselect_b32 s3, 4, 0
	s_cselect_b32 s25, 1, 0
	s_add_u32 s40, s40, s2
	s_addc_u32 s41, s41, 0
	s_add_u32 s42, s42, s3
	s_addc_u32 s43, s43, 0
	s_add_u32 s46, s46, s25
	global_load_dwordx4 v[40:43], v186, s[40:41]
	global_load_dwordx4 v[44:47], v187, s[40:41]
	global_load_dwordx4 v[48:51], v187, s[40:41] offset:64
	global_load_dwordx4 v[60:63], v189, s[40:41]
	global_load_dwordx4 v[64:67], v189, s[40:41] offset:64
	global_load_dwordx4 v[52:55], v188, s[40:41]
	global_load_dwordx4 v[56:59], v188, s[40:41] offset:64
	global_load_dwordx4 v[68:71], v190, s[40:41]
	global_load_dwordx4 v[72:75], v190, s[40:41] offset:64
	global_load_dword v76, v129, s[42:43]
	s_cmp_lt_u32 s46, 0xff
	s_cselect_b32 s2, 0xc000, 0
	s_cselect_b32 s3, 4, 0
	s_cselect_b32 s25, 1, 0
	s_add_u32 s40, s40, s2
	s_addc_u32 s41, s41, 0
	s_add_u32 s42, s42, s3
	s_addc_u32 s43, s43, 0
	s_add_u32 s46, s46, s25
	global_load_dwordx4 v[80:83], v186, s[40:41]
	global_load_dwordx4 v[84:87], v187, s[40:41]
	global_load_dwordx4 v[88:91], v187, s[40:41] offset:64
	global_load_dwordx4 v[100:103], v189, s[40:41]
	global_load_dwordx4 v[104:107], v189, s[40:41] offset:64
	global_load_dwordx4 v[92:95], v188, s[40:41]
	global_load_dwordx4 v[96:99], v188, s[40:41] offset:64
	global_load_dwordx4 v[108:111], v190, s[40:41]
	global_load_dwordx4 v[112:115], v190, s[40:41] offset:64
	global_load_dword v116, v129, s[42:43]
	s_cmp_lt_u32 s46, 0xff
	s_cselect_b32 s2, 0xc000, 0
	s_cselect_b32 s3, 4, 0
	s_cselect_b32 s25, 1, 0
	s_add_u32 s40, s40, s2
	s_addc_u32 s41, s41, 0
	s_add_u32 s42, s42, s3
	s_addc_u32 s43, s43, 0
	s_add_u32 s46, s46, s25
	s_waitcnt lgkmcnt(0)
	s_barrier
	ds_read_b128 v[176:179], v192
	ds_read_b128 v[180:183], v192 offset:64
	global_load_dwordx4 v[130:133], v186, s[40:41]
	global_load_dwordx4 v[134:137], v187, s[40:41]
	global_load_dwordx4 v[138:141], v187, s[40:41] offset:64
	global_load_dwordx4 v[150:153], v189, s[40:41]
	global_load_dwordx4 v[154:157], v189, s[40:41] offset:64
	global_load_dwordx4 v[142:145], v188, s[40:41]
	global_load_dwordx4 v[146:149], v188, s[40:41] offset:64
	global_load_dwordx4 v[158:161], v190, s[40:41]
	global_load_dwordx4 v[162:165], v190, s[40:41] offset:64
	global_load_dword v166, v129, s[42:43]
	s_cmp_lt_u32 s46, 0xff
	s_cselect_b32 s2, 0xc000, 0
	s_cselect_b32 s3, 4, 0
	s_cselect_b32 s25, 1, 0
	s_add_u32 s40, s40, s2
	s_addc_u32 s41, s41, 0
	s_add_u32 s42, s42, s3
	s_addc_u32 s43, s43, 0
	s_add_u32 s46, s46, s25
	s_waitcnt vmcnt(30)
	v_mul_f32_e32 v168, v168, v36
	v_mul_f32_e32 v169, v169, v36
	v_mul_f32_e32 v170, v170, v36
	v_mul_f32_e32 v171, v171, v36
	s_waitcnt lgkmcnt(1)
	v_mfma_f32_16x16x32_bf16 v[0:3], v[4:7], v[176:179], v[0:3]
	s_waitcnt lgkmcnt(0)
	v_mfma_f32_16x16x32_bf16 v[0:3], v[8:11], v[180:183], v[0:3]
	v_mfma_f32_16x16x32_bf16 v[172:175], v[12:15], v[176:179], 0
	v_mfma_f32_16x16x32_bf16 v[172:175], v[16:19], v[180:183], v[172:175]
	s_nop 5
	v_cvt_pk_bf16_f32 v184, v0, v1
	v_cvt_pk_bf16_f32 v185, v2, v3
	ds_write_b64 v191, v[184:185] offset:2304
	s_waitcnt lgkmcnt(0)
	s_barrier
	ds_read_b128 v[176:179], v192 offset:2304
	ds_read_b128 v[180:183], v192 offset:2368
	s_waitcnt lgkmcnt(1)
	v_mfma_f32_16x16x32_bf16 v[168:171], v[20:23], v[176:179], v[168:171]
	s_waitcnt lgkmcnt(0)
	v_mfma_f32_16x16x32_bf16 v[168:171], v[24:27], v[180:183], v[168:171]
	v_mfma_f32_16x16x32_bf16 v[172:175], v[28:31], v[176:179], v[172:175]
	v_mfma_f32_16x16x32_bf16 v[172:175], v[32:35], v[180:183], v[172:175]
	s_nop 5
	v_cvt_pk_bf16_f32 v184, v168, v169
	v_cvt_pk_bf16_f32 v185, v170, v171
	ds_write_b64 v191, v[184:185]
	s_waitcnt lgkmcnt(0)
	s_barrier
	ds_read_b128 v[176:179], v192
	ds_read_b128 v[180:183], v192 offset:64
	global_store_dword v193, v172, s[44:45]
	global_store_dword v193, v173, s[44:45] offset:1024
	global_store_dword v193, v174, s[44:45] offset:2048
	global_store_dword v193, v175, s[44:45] offset:3072
	s_add_u32 s44, s44, 0x10000
	s_addc_u32 s45, s45, 0
	global_load_dwordx4 v[0:3], v186, s[40:41]
	global_load_dwordx4 v[4:7], v187, s[40:41]
	global_load_dwordx4 v[8:11], v187, s[40:41] offset:64
	global_load_dwordx4 v[20:23], v189, s[40:41]
	global_load_dwordx4 v[24:27], v189, s[40:41] offset:64
	global_load_dwordx4 v[12:15], v188, s[40:41]
	global_load_dwordx4 v[16:19], v188, s[40:41] offset:64
	global_load_dwordx4 v[28:31], v190, s[40:41]
	global_load_dwordx4 v[32:35], v190, s[40:41] offset:64
	global_load_dword v36, v129, s[42:43]
	s_cmp_lt_u32 s46, 0xff
	s_cselect_b32 s2, 0xc000, 0
	s_cselect_b32 s3, 4, 0
	s_cselect_b32 s25, 1, 0
	s_add_u32 s40, s40, s2
	s_addc_u32 s41, s41, 0
	s_add_u32 s42, s42, s3
	s_addc_u32 s43, s43, 0
	s_add_u32 s46, s46, s25
	s_waitcnt vmcnt(34)
	v_mul_f32_e32 v168, v168, v76
	v_mul_f32_e32 v169, v169, v76
	v_mul_f32_e32 v170, v170, v76
	v_mul_f32_e32 v171, v171, v76
	s_waitcnt lgkmcnt(1)
	v_mfma_f32_16x16x32_bf16 v[40:43], v[44:47], v[176:179], v[40:43]
	s_waitcnt lgkmcnt(0)
	v_mfma_f32_16x16x32_bf16 v[40:43], v[48:51], v[180:183], v[40:43]
	v_mfma_f32_16x16x32_bf16 v[172:175], v[52:55], v[176:179], 0
	v_mfma_f32_16x16x32_bf16 v[172:175], v[56:59], v[180:183], v[172:175]
	s_nop 5
	v_cvt_pk_bf16_f32 v184, v40, v41
	v_cvt_pk_bf16_f32 v185, v42, v43
	ds_write_b64 v191, v[184:185] offset:2304
	s_waitcnt lgkmcnt(0)
	s_barrier
	ds_read_b128 v[176:179], v192 offset:2304
	ds_read_b128 v[180:183], v192 offset:2368
	s_waitcnt lgkmcnt(1)
	v_mfma_f32_16x16x32_bf16 v[168:171], v[60:63], v[176:179], v[168:171]
	s_waitcnt lgkmcnt(0)
	v_mfma_f32_16x16x32_bf16 v[168:171], v[64:67], v[180:183], v[168:171]
	v_mfma_f32_16x16x32_bf16 v[172:175], v[68:71], v[176:179], v[172:175]
	v_mfma_f32_16x16x32_bf16 v[172:175], v[72:75], v[180:183], v[172:175]
	s_nop 5
	v_cvt_pk_bf16_f32 v184, v168, v169
	v_cvt_pk_bf16_f32 v185, v170, v171
	ds_write_b64 v191, v[184:185]
	s_waitcnt lgkmcnt(0)
	s_barrier
	ds_read_b128 v[176:179], v192
	ds_read_b128 v[180:183], v192 offset:64
	global_store_dword v193, v172, s[44:45]
	global_store_dword v193, v173, s[44:45] offset:1024
	global_store_dword v193, v174, s[44:45] offset:2048
	global_store_dword v193, v175, s[44:45] offset:3072
	s_add_u32 s44, s44, 0x10000
	s_addc_u32 s45, s45, 0
	global_load_dwordx4 v[40:43], v186, s[40:41]
	global_load_dwordx4 v[44:47], v187, s[40:41]
	global_load_dwordx4 v[48:51], v187, s[40:41] offset:64
	global_load_dwordx4 v[60:63], v189, s[40:41]
	global_load_dwordx4 v[64:67], v189, s[40:41] offset:64
	global_load_dwordx4 v[52:55], v188, s[40:41]
	global_load_dwordx4 v[56:59], v188, s[40:41] offset:64
	global_load_dwordx4 v[68:71], v190, s[40:41]
	global_load_dwordx4 v[72:75], v190, s[40:41] offset:64
	global_load_dword v76, v129, s[42:43]
	s_cmp_lt_u32 s46, 0xff
	s_cselect_b32 s2, 0xc000, 0
	s_cselect_b32 s3, 4, 0
	s_cselect_b32 s25, 1, 0
	s_add_u32 s40, s40, s2
	s_addc_u32 s41, s41, 0
	s_add_u32 s42, s42, s3
	s_addc_u32 s43, s43, 0
	s_add_u32 s46, s46, s25
	s_waitcnt vmcnt(38)
	v_mul_f32_e32 v168, v168, v116
	v_mul_f32_e32 v169, v169, v116
	v_mul_f32_e32 v170, v170, v116
	v_mul_f32_e32 v171, v171, v116
	s_waitcnt lgkmcnt(1)
	v_mfma_f32_16x16x32_bf16 v[80:83], v[84:87], v[176:179], v[80:83]
	s_waitcnt lgkmcnt(0)
	v_mfma_f32_16x16x32_bf16 v[80:83], v[88:91], v[180:183], v[80:83]
	v_mfma_f32_16x16x32_bf16 v[172:175], v[92:95], v[176:179], 0
	v_mfma_f32_16x16x32_bf16 v[172:175], v[96:99], v[180:183], v[172:175]
	s_nop 5
	v_cvt_pk_bf16_f32 v184, v80, v81
	v_cvt_pk_bf16_f32 v185, v82, v83
	ds_write_b64 v191, v[184:185] offset:2304
	s_waitcnt lgkmcnt(0)
	s_barrier
	ds_read_b128 v[176:179], v192 offset:2304
	ds_read_b128 v[180:183], v192 offset:2368
	s_waitcnt lgkmcnt(1)
	v_mfma_f32_16x16x32_bf16 v[168:171], v[100:103], v[176:179], v[168:171]
	s_waitcnt lgkmcnt(0)
	v_mfma_f32_16x16x32_bf16 v[168:171], v[104:107], v[180:183], v[168:171]
	v_mfma_f32_16x16x32_bf16 v[172:175], v[108:111], v[176:179], v[172:175]
	v_mfma_f32_16x16x32_bf16 v[172:175], v[112:115], v[180:183], v[172:175]
	s_nop 5
	v_cvt_pk_bf16_f32 v184, v168, v169
	v_cvt_pk_bf16_f32 v185, v170, v171
	ds_write_b64 v191, v[184:185]
	s_waitcnt lgkmcnt(0)
	s_barrier
	ds_read_b128 v[176:179], v192
	ds_read_b128 v[180:183], v192 offset:64
	global_store_dword v193, v172, s[44:45]
	global_store_dword v193, v173, s[44:45] offset:1024
	global_store_dword v193, v174, s[44:45] offset:2048
	global_store_dword v193, v175, s[44:45] offset:3072
	s_add_u32 s44, s44, 0x10000
	s_addc_u32 s45, s45, 0
	global_load_dwordx4 v[80:83], v186, s[40:41]
	global_load_dwordx4 v[84:87], v187, s[40:41]
	global_load_dwordx4 v[88:91], v187, s[40:41] offset:64
	global_load_dwordx4 v[100:103], v189, s[40:41]
	global_load_dwordx4 v[104:107], v189, s[40:41] offset:64
	global_load_dwordx4 v[92:95], v188, s[40:41]
	global_load_dwordx4 v[96:99], v188, s[40:41] offset:64
	global_load_dwordx4 v[108:111], v190, s[40:41]
	global_load_dwordx4 v[112:115], v190, s[40:41] offset:64
	global_load_dword v116, v129, s[42:43]
	s_cmp_lt_u32 s46, 0xff
	s_cselect_b32 s2, 0xc000, 0
	s_cselect_b32 s3, 4, 0
	s_cselect_b32 s25, 1, 0
	s_add_u32 s40, s40, s2
	s_addc_u32 s41, s41, 0
	s_add_u32 s42, s42, s3
	s_addc_u32 s43, s43, 0
	s_add_u32 s46, s46, s25
	s_waitcnt vmcnt(42)
	v_mul_f32_e32 v168, v168, v166
	v_mul_f32_e32 v169, v169, v166
	v_mul_f32_e32 v170, v170, v166
	v_mul_f32_e32 v171, v171, v166
	s_waitcnt lgkmcnt(1)
	v_mfma_f32_16x16x32_bf16 v[130:133], v[134:137], v[176:179], v[130:133]
	s_waitcnt lgkmcnt(0)
	v_mfma_f32_16x16x32_bf16 v[130:133], v[138:141], v[180:183], v[130:133]
	v_mfma_f32_16x16x32_bf16 v[172:175], v[142:145], v[176:179], 0
	v_mfma_f32_16x16x32_bf16 v[172:175], v[146:149], v[180:183], v[172:175]
	s_nop 5
	v_cvt_pk_bf16_f32 v184, v130, v131
	v_cvt_pk_bf16_f32 v185, v132, v133
	ds_write_b64 v191, v[184:185] offset:2304
	s_waitcnt lgkmcnt(0)
	s_barrier
	ds_read_b128 v[176:179], v192 offset:2304
	ds_read_b128 v[180:183], v192 offset:2368
	s_waitcnt lgkmcnt(1)
	v_mfma_f32_16x16x32_bf16 v[168:171], v[150:153], v[176:179], v[168:171]
	s_waitcnt lgkmcnt(0)
	v_mfma_f32_16x16x32_bf16 v[168:171], v[154:157], v[180:183], v[168:171]
	v_mfma_f32_16x16x32_bf16 v[172:175], v[158:161], v[176:179], v[172:175]
	v_mfma_f32_16x16x32_bf16 v[172:175], v[162:165], v[180:183], v[172:175]
	s_nop 5
	v_cvt_pk_bf16_f32 v184, v168, v169
	v_cvt_pk_bf16_f32 v185, v170, v171
	ds_write_b64 v191, v[184:185]
	s_waitcnt lgkmcnt(0)
	s_barrier
	s_mov_b32 s47, 63
.Lscan_round:
	ds_read_b128 v[176:179], v192
	ds_read_b128 v[180:183], v192 offset:64
	global_store_dword v193, v172, s[44:45]
	global_store_dword v193, v173, s[44:45] offset:1024
	global_store_dword v193, v174, s[44:45] offset:2048
	global_store_dword v193, v175, s[44:45] offset:3072
	s_add_u32 s44, s44, 0x10000
	s_addc_u32 s45, s45, 0
	global_load_dwordx4 v[130:133], v186, s[40:41]
	global_load_dwordx4 v[134:137], v187, s[40:41]
	global_load_dwordx4 v[138:141], v187, s[40:41] offset:64
	global_load_dwordx4 v[150:153], v189, s[40:41]
	global_load_dwordx4 v[154:157], v189, s[40:41] offset:64
	global_load_dwordx4 v[142:145], v188, s[40:41]
	global_load_dwordx4 v[146:149], v188, s[40:41] offset:64
	global_load_dwordx4 v[158:161], v190, s[40:41]
	global_load_dwordx4 v[162:165], v190, s[40:41] offset:64
	global_load_dword v166, v129, s[42:43]
	s_cmp_lt_u32 s46, 0xff
	s_cselect_b32 s2, 0xc000, 0
	s_cselect_b32 s3, 4, 0
	s_cselect_b32 s25, 1, 0
	s_add_u32 s40, s40, s2
	s_addc_u32 s41, s41, 0
	s_add_u32 s42, s42, s3
	s_addc_u32 s43, s43, 0
	s_add_u32 s46, s46, s25
	s_waitcnt vmcnt(42)
	v_mul_f32_e32 v168, v168, v36
	v_mul_f32_e32 v169, v169, v36
	v_mul_f32_e32 v170, v170, v36
	v_mul_f32_e32 v171, v171, v36
	s_waitcnt lgkmcnt(1)
	v_mfma_f32_16x16x32_bf16 v[0:3], v[4:7], v[176:179], v[0:3]
	s_waitcnt lgkmcnt(0)
	v_mfma_f32_16x16x32_bf16 v[0:3], v[8:11], v[180:183], v[0:3]
	v_mfma_f32_16x16x32_bf16 v[172:175], v[12:15], v[176:179], 0
	v_mfma_f32_16x16x32_bf16 v[172:175], v[16:19], v[180:183], v[172:175]
	s_nop 5
	v_cvt_pk_bf16_f32 v184, v0, v1
	v_cvt_pk_bf16_f32 v185, v2, v3
	ds_write_b64 v191, v[184:185] offset:2304
	s_waitcnt lgkmcnt(0)
	s_barrier
	ds_read_b128 v[176:179], v192 offset:2304
	ds_read_b128 v[180:183], v192 offset:2368
	s_waitcnt lgkmcnt(1)
	v_mfma_f32_16x16x32_bf16 v[168:171], v[20:23], v[176:179], v[168:171]
	s_waitcnt lgkmcnt(0)
	v_mfma_f32_16x16x32_bf16 v[168:171], v[24:27], v[180:183], v[168:171]
	v_mfma_f32_16x16x32_bf16 v[172:175], v[28:31], v[176:179], v[172:175]
	v_mfma_f32_16x16x32_bf16 v[172:175], v[32:35], v[180:183], v[172:175]
	s_nop 5
	v_cvt_pk_bf16_f32 v184, v168, v169
	v_cvt_pk_bf16_f32 v185, v170, v171
	ds_write_b64 v191, v[184:185]
	s_waitcnt lgkmcnt(0)
	s_barrier
	ds_read_b128 v[176:179], v192
	ds_read_b128 v[180:183], v192 offset:64
	global_store_dword v193, v172, s[44:45]
	global_store_dword v193, v173, s[44:45] offset:1024
	global_store_dword v193, v174, s[44:45] offset:2048
	global_store_dword v193, v175, s[44:45] offset:3072
	s_add_u32 s44, s44, 0x10000
	s_addc_u32 s45, s45, 0
	global_load_dwordx4 v[0:3], v186, s[40:41]
	global_load_dwordx4 v[4:7], v187, s[40:41]
	global_load_dwordx4 v[8:11], v187, s[40:41] offset:64
	global_load_dwordx4 v[20:23], v189, s[40:41]
	global_load_dwordx4 v[24:27], v189, s[40:41] offset:64
	global_load_dwordx4 v[12:15], v188, s[40:41]
	global_load_dwordx4 v[16:19], v188, s[40:41] offset:64
	global_load_dwordx4 v[28:31], v190, s[40:41]
	global_load_dwordx4 v[32:35], v190, s[40:41] offset:64
	global_load_dword v36, v129, s[42:43]
	s_cmp_lt_u32 s46, 0xff
	s_cselect_b32 s2, 0xc000, 0
	s_cselect_b32 s3, 4, 0
	s_cselect_b32 s25, 1, 0
	s_add_u32 s40, s40, s2
	s_addc_u32 s41, s41, 0
	s_add_u32 s42, s42, s3
	s_addc_u32 s43, s43, 0
	s_add_u32 s46, s46, s25
	s_waitcnt vmcnt(42)
	v_mul_f32_e32 v168, v168, v76
	v_mul_f32_e32 v169, v169, v76
	v_mul_f32_e32 v170, v170, v76
	v_mul_f32_e32 v171, v171, v76
	s_waitcnt lgkmcnt(1)
	v_mfma_f32_16x16x32_bf16 v[40:43], v[44:47], v[176:179], v[40:43]
	s_waitcnt lgkmcnt(0)
	v_mfma_f32_16x16x32_bf16 v[40:43], v[48:51], v[180:183], v[40:43]
	v_mfma_f32_16x16x32_bf16 v[172:175], v[52:55], v[176:179], 0
	v_mfma_f32_16x16x32_bf16 v[172:175], v[56:59], v[180:183], v[172:175]
	s_nop 5
	v_cvt_pk_bf16_f32 v184, v40, v41
	v_cvt_pk_bf16_f32 v185, v42, v43
	ds_write_b64 v191, v[184:185] offset:2304
	s_waitcnt lgkmcnt(0)
	s_barrier
	ds_read_b128 v[176:179], v192 offset:2304
	ds_read_b128 v[180:183], v192 offset:2368
	s_waitcnt lgkmcnt(1)
	v_mfma_f32_16x16x32_bf16 v[168:171], v[60:63], v[176:179], v[168:171]
	s_waitcnt lgkmcnt(0)
	v_mfma_f32_16x16x32_bf16 v[168:171], v[64:67], v[180:183], v[168:171]
	v_mfma_f32_16x16x32_bf16 v[172:175], v[68:71], v[176:179], v[172:175]
	v_mfma_f32_16x16x32_bf16 v[172:175], v[72:75], v[180:183], v[172:175]
	s_nop 5
	v_cvt_pk_bf16_f32 v184, v168, v169
	v_cvt_pk_bf16_f32 v185, v170, v171
	ds_write_b64 v191, v[184:185]
	s_waitcnt lgkmcnt(0)
	s_barrier
	ds_read_b128 v[176:179], v192
	ds_read_b128 v[180:183], v192 offset:64
	global_store_dword v193, v172, s[44:45]
	global_store_dword v193, v173, s[44:45] offset:1024
	global_store_dword v193, v174, s[44:45] offset:2048
	global_store_dword v193, v175, s[44:45] offset:3072
	s_add_u32 s44, s44, 0x10000
	s_addc_u32 s45, s45, 0
	global_load_dwordx4 v[40:43], v186, s[40:41]
	global_load_dwordx4 v[44:47], v187, s[40:41]
	global_load_dwordx4 v[48:51], v187, s[40:41] offset:64
	global_load_dwordx4 v[60:63], v189, s[40:41]
	global_load_dwordx4 v[64:67], v189, s[40:41] offset:64
	global_load_dwordx4 v[52:55], v188, s[40:41]
	global_load_dwordx4 v[56:59], v188, s[40:41] offset:64
	global_load_dwordx4 v[68:71], v190, s[40:41]
	global_load_dwordx4 v[72:75], v190, s[40:41] offset:64
	global_load_dword v76, v129, s[42:43]
	s_cmp_lt_u32 s46, 0xff
	s_cselect_b32 s2, 0xc000, 0
	s_cselect_b32 s3, 4, 0
	s_cselect_b32 s25, 1, 0
	s_add_u32 s40, s40, s2
	s_addc_u32 s41, s41, 0
	s_add_u32 s42, s42, s3
	s_addc_u32 s43, s43, 0
	s_add_u32 s46, s46, s25
	s_waitcnt vmcnt(42)
	v_mul_f32_e32 v168, v168, v116
	v_mul_f32_e32 v169, v169, v116
	v_mul_f32_e32 v170, v170, v116
	v_mul_f32_e32 v171, v171, v116
	s_waitcnt lgkmcnt(1)
	v_mfma_f32_16x16x32_bf16 v[80:83], v[84:87], v[176:179], v[80:83]
	s_waitcnt lgkmcnt(0)
	v_mfma_f32_16x16x32_bf16 v[80:83], v[88:91], v[180:183], v[80:83]
	v_mfma_f32_16x16x32_bf16 v[172:175], v[92:95], v[176:179], 0
	v_mfma_f32_16x16x32_bf16 v[172:175], v[96:99], v[180:183], v[172:175]
	s_nop 5
	v_cvt_pk_bf16_f32 v184, v80, v81
	v_cvt_pk_bf16_f32 v185, v82, v83
	ds_write_b64 v191, v[184:185] offset:2304
	s_waitcnt lgkmcnt(0)
	s_barrier
	ds_read_b128 v[176:179], v192 offset:2304
	ds_read_b128 v[180:183], v192 offset:2368
	s_waitcnt lgkmcnt(1)
	v_mfma_f32_16x16x32_bf16 v[168:171], v[100:103], v[176:179], v[168:171]
	s_waitcnt lgkmcnt(0)
	v_mfma_f32_16x16x32_bf16 v[168:171], v[104:107], v[180:183], v[168:171]
	v_mfma_f32_16x16x32_bf16 v[172:175], v[108:111], v[176:179], v[172:175]
	v_mfma_f32_16x16x32_bf16 v[172:175], v[112:115], v[180:183], v[172:175]
	s_nop 5
	v_cvt_pk_bf16_f32 v184, v168, v169
	v_cvt_pk_bf16_f32 v185, v170, v171
	ds_write_b64 v191, v[184:185]
	s_waitcnt lgkmcnt(0)
	s_barrier
	ds_read_b128 v[176:179], v192
	ds_read_b128 v[180:183], v192 offset:64
	global_store_dword v193, v172, s[44:45]
	global_store_dword v193, v173, s[44:45] offset:1024
	global_store_dword v193, v174, s[44:45] offset:2048
	global_store_dword v193, v175, s[44:45] offset:3072
	s_add_u32 s44, s44, 0x10000
	s_addc_u32 s45, s45, 0
	global_load_dwordx4 v[80:83], v186, s[40:41]
	global_load_dwordx4 v[84:87], v187, s[40:41]
	global_load_dwordx4 v[88:91], v187, s[40:41] offset:64
	global_load_dwordx4 v[100:103], v189, s[40:41]
	global_load_dwordx4 v[104:107], v189, s[40:41] offset:64
	global_load_dwordx4 v[92:95], v188, s[40:41]
	global_load_dwordx4 v[96:99], v188, s[40:41] offset:64
	global_load_dwordx4 v[108:111], v190, s[40:41]
	global_load_dwordx4 v[112:115], v190, s[40:41] offset:64
	global_load_dword v116, v129, s[42:43]
	s_cmp_lt_u32 s46, 0xff
	s_cselect_b32 s2, 0xc000, 0
	s_cselect_b32 s3, 4, 0
	s_cselect_b32 s25, 1, 0
	s_add_u32 s40, s40, s2
	s_addc_u32 s41, s41, 0
	s_add_u32 s42, s42, s3
	s_addc_u32 s43, s43, 0
	s_add_u32 s46, s46, s25
	s_waitcnt vmcnt(42)
	v_mul_f32_e32 v168, v168, v166
	v_mul_f32_e32 v169, v169, v166
	v_mul_f32_e32 v170, v170, v166
	v_mul_f32_e32 v171, v171, v166
	s_waitcnt lgkmcnt(1)
	v_mfma_f32_16x16x32_bf16 v[130:133], v[134:137], v[176:179], v[130:133]
	s_waitcnt lgkmcnt(0)
	v_mfma_f32_16x16x32_bf16 v[130:133], v[138:141], v[180:183], v[130:133]
	v_mfma_f32_16x16x32_bf16 v[172:175], v[142:145], v[176:179], 0
	v_mfma_f32_16x16x32_bf16 v[172:175], v[146:149], v[180:183], v[172:175]
	s_nop 5
	v_cvt_pk_bf16_f32 v184, v130, v131
	v_cvt_pk_bf16_f32 v185, v132, v133
	ds_write_b64 v191, v[184:185] offset:2304
	s_waitcnt lgkmcnt(0)
	s_barrier
	ds_read_b128 v[176:179], v192 offset:2304
	ds_read_b128 v[180:183], v192 offset:2368
	s_waitcnt lgkmcnt(1)
	v_mfma_f32_16x16x32_bf16 v[168:171], v[150:153], v[176:179], v[168:171]
	s_waitcnt lgkmcnt(0)
	v_mfma_f32_16x16x32_bf16 v[168:171], v[154:157], v[180:183], v[168:171]
	v_mfma_f32_16x16x32_bf16 v[172:175], v[158:161], v[176:179], v[172:175]
	v_mfma_f32_16x16x32_bf16 v[172:175], v[162:165], v[180:183], v[172:175]
	s_nop 5
	v_cvt_pk_bf16_f32 v184, v168, v169
	v_cvt_pk_bf16_f32 v185, v170, v171
	ds_write_b64 v191, v[184:185]
	s_waitcnt lgkmcnt(0)
	s_barrier
	s_sub_u32 s47, s47, 1
	s_cmp_lg_u32 s47, 0
	s_cbranch_scc1 .Lscan_round
	global_store_dword v193, v172, s[44:45]
	global_store_dword v193, v173, s[44:45] offset:1024
	global_store_dword v193, v174, s[44:45] offset:2048
	global_store_dword v193, v175, s[44:45] offset:3072
	s_add_u32 s44, s44, 0x10000
	s_addc_u32 s45, s45, 0
	s_waitcnt vmcnt(0)
	s_setprio 0
.LBB0_637:
	s_lshr_b32 s50, s82, 1
	s_and_b32 s50, s50, 3
	v_writelane_b32 v255, s50, 51
	s_load_dwordx2 s[36:37], s[36:37], 0x98
	s_waitcnt lgkmcnt(0)
	s_add_u32 s38, s36, 0x1f510000
	s_addc_u32 s39, s37, 0
	s_add_u32 s52, s36, 0x4000000
	s_addc_u32 s53, s37, 0
	s_add_u32 s54, s36, 0x1f300000
	s_addc_u32 s55, s37, 0
	s_add_u32 s56, s36, 0x1f100000
	s_addc_u32 s57, s37, 0
	s_add_u32 s58, s36, 0x10000000
	s_addc_u32 s59, s37, 0
	s_add_u32 s60, s36, 0x1a000000
	s_addc_u32 s61, s37, 0
	s_add_u32 s25, s36, 0x1e800000
	s_addc_u32 s66, s37, 0
	s_add_u32 s67, s36, 0x1e000000
	s_addc_u32 s68, s37, 0
	s_add_u32 s62, s36, 0x1e006000
	s_addc_u32 s63, s37, 0
	s_branch .LBB0_640

.LBB0_640:
	s_barrier
	s_mov_b64 s[40:41], exec
	v_readlane_b32 s2, v254, 4
	v_readlane_b32 s3, v254, 5
	s_and_b64 s[2:3], s[40:41], s[2:3]
	s_mov_b64 exec, s[2:3]
	s_cbranch_execz .LBB0_644
	v_readlane_b32 s42, v255, 51
	s_mov_b32 s43, 0
.Ltq_retry:
	s_lshl_b32 s2, s42, 2
	v_mov_b32_e32 v0, s2
	v_mov_b32_e32 v1, 1
	global_atomic_add v1, v0, v1, s[38:39] sc0
	s_waitcnt vmcnt(0)
	v_readfirstlane_b32 s2, v1
	s_cmp_lt_u32 s2, 0x100
	s_cbranch_scc1 .Ltq_got
	s_add_u32 s42, s42, 1
	s_and_b32 s42, s42, 3
	s_add_u32 s43, s43, 1
	s_cmp_lt_u32 s43, 4
	s_cbranch_scc1 .Ltq_retry
	s_movk_i32 s2, 0x400
	s_branch .Ltq_store
.Ltq_got:
	s_lshl_b32 s2, s2, 2
	s_or_b32 s2, s2, s42
.Ltq_store:
	v_writelane_b32 v255, s42, 51
	v_mov_b32_e32 v0, s2
	ds_write_b32 v226, v0

.LBB0_760:
	s_and_b32 s2, s42, 30
	s_lshl_b32 s70, 1, s2
	s_cmp_lg_u32 s2, 0
	s_cbranch_scc1 .Lsel_have_words
	s_lshr_b32 s2, s42, 3
	s_and_b32 s2, s2, 0x1ffffffc
	v_add_u32_e32 v248, s2, v245
	ds_read2_b32 v[250:251], v248 offset1:32
	ds_read_b32 v249, v248 offset:256
	ds_read_b32 v248, v248 offset:384
	s_waitcnt lgkmcnt(0)
.Lsel_have_words:
	v_and_b32_e32 v0, s70, v250
	v_cmp_ne_u32_e64 s[50:51], 0, v0
	v_and_b32_e32 v0, s70, v251
	v_cmp_ne_u32_e64 s[48:49], 0, v0
	v_and_b32_e32 v0, s70, v249
	v_cmp_ne_u32_e64 s[46:47], 0, v0
	v_and_b32_e32 v0, s70, v248
	v_cmp_ne_u32_e64 s[42:43], 0, v0
	s_mov_b64 s[86:87], s[50:51]
	s_mov_b64 s[88:89], s[48:49]
	s_mov_b64 s[90:91], s[46:47]
	s_mov_b64 s[92:93], s[42:43]
	s_or_b64 s[2:3], s[48:49], s[50:51]
	s_or_b64 s[2:3], s[2:3], s[46:47]
	s_or_b64 s[2:3], s[2:3], s[42:43]
	s_cmp_eq_u64 s[2:3], 0
	s_cbranch_scc1 .LBB0_785
	ds_read_b128 v[182:185], v246
	ds_read_b128 v[178:181], v246 offset:2048
	ds_read_b128 v[186:189], v247
	ds_read_b128 v[174:177], v247 offset:2048
	ds_read_b128 v[158:161], v244 offset:4096
	ds_read_b128 v[162:165], v244 offset:5120
	ds_read_b128 v[166:169], v244 offset:6144
	ds_read_b128 v[170:173], v244 offset:7168
	s_add_i32 s2, s28, 0xfffffeff
	s_cmp_le_i32 s2, s26
	s_cselect_b64 s[2:3], -1, 0
	v_cndmask_b32_e64 v0, 0, 1, s[2:3]
	s_cmp_eq_u64 s[50:51], 0
	v_cmp_ne_u32_e64 s[44:45], 1, v0
	s_cbranch_scc1 .LBB0_767
	s_waitcnt lgkmcnt(7)
	v_mfma_f32_16x16x32_bf16 v[0:3], v[182:185], v[104:107], 0
	s_and_b64 vcc, exec, s[44:45]
	s_mov_b64 s[64:65], -1
	s_waitcnt lgkmcnt(6)
	v_mfma_f32_16x16x32_bf16 v[4:7], v[178:181], v[104:107], 0
	s_waitcnt lgkmcnt(5)
	v_mfma_f32_16x16x32_bf16 v[0:3], v[186:189], v[108:111], v[0:3]
	s_waitcnt lgkmcnt(4)
	v_mfma_f32_16x16x32_bf16 v[4:7], v[174:177], v[108:111], v[4:7]
	s_nop 5
	v_exp_f32_e32 v0, v0
	v_exp_f32_e32 v1, v1
	v_exp_f32_e32 v2, v2
	v_exp_f32_e32 v3, v3
	v_exp_f32_e32 v4, v4
	v_exp_f32_e32 v5, v5
	v_exp_f32_e32 v6, v6
	v_exp_f32_e32 v7, v7
	s_cbranch_vccnz .LBB0_764
	s_mov_b64 s[64:65], 0

.LBB0_785:
	s_mov_b64 s[50:51], s[86:87]
	s_mov_b64 s[48:49], s[88:89]
	s_mov_b64 s[46:47], s[90:91]
	s_mov_b64 s[42:43], s[92:93]
	s_or_b64 s[2:3], s[48:49], s[50:51]
	s_or_b64 s[2:3], s[2:3], s[46:47]
	s_or_b64 s[2:3], s[2:3], s[42:43]
	s_cmp_eq_u64 s[2:3], 0
	s_cbranch_scc1 .LBB0_810
	ds_read_b128 v[182:185], v246 offset:8192
	ds_read_b128 v[178:181], v246 offset:10240
	ds_read_b128 v[186:189], v247 offset:8192
	ds_read_b128 v[174:177], v247 offset:10240
	ds_read_b128 v[158:161], v244 offset:12288
	ds_read_b128 v[162:165], v244 offset:13312
	ds_read_b128 v[166:169], v244 offset:14336
	ds_read_b128 v[170:173], v244 offset:15360
	s_add_i32 s2, s28, 0xffffff1f
	s_cmp_le_i32 s2, s26
	s_cselect_b64 s[2:3], -1, 0
	v_cndmask_b32_e64 v0, 0, 1, s[2:3]
	s_cmp_eq_u64 s[50:51], 0
	v_cmp_ne_u32_e64 s[44:45], 1, v0
	s_cbranch_scc1 .LBB0_792
	s_waitcnt lgkmcnt(7)
	v_mfma_f32_16x16x32_bf16 v[0:3], v[182:185], v[104:107], 0
	s_and_b64 vcc, exec, s[44:45]
	s_mov_b64 s[64:65], -1
	s_waitcnt lgkmcnt(6)
	v_mfma_f32_16x16x32_bf16 v[4:7], v[178:181], v[104:107], 0
	s_waitcnt lgkmcnt(5)
	v_mfma_f32_16x16x32_bf16 v[0:3], v[186:189], v[108:111], v[0:3]
	s_waitcnt lgkmcnt(4)
	v_mfma_f32_16x16x32_bf16 v[4:7], v[174:177], v[108:111], v[4:7]
	s_nop 5
	v_exp_f32_e32 v0, v0
	v_exp_f32_e32 v1, v1
	v_exp_f32_e32 v2, v2
	v_exp_f32_e32 v3, v3
	v_exp_f32_e32 v4, v4
	v_exp_f32_e32 v5, v5
	v_exp_f32_e32 v6, v6
	v_exp_f32_e32 v7, v7
	s_cbranch_vccnz .LBB0_789
	s_mov_b64 s[64:65], 0

.LBB0_815:
	s_add_i32 s2, s27, -3
	s_lshl_b32 s64, 1, s2
	v_and_b32_e32 v0, s64, v250
	v_cmp_ne_u32_e64 s[50:51], 0, v0
	v_and_b32_e32 v0, s64, v251
	v_cmp_ne_u32_e64 s[48:49], 0, v0
	v_and_b32_e32 v0, s64, v249
	v_cmp_ne_u32_e64 s[46:47], 0, v0
	v_and_b32_e32 v0, s64, v248
	v_cmp_ne_u32_e64 s[42:43], 0, v0
	s_mov_b64 s[86:87], s[50:51]
	s_mov_b64 s[88:89], s[48:49]
	s_mov_b64 s[90:91], s[46:47]
	s_mov_b64 s[92:93], s[42:43]
	s_or_b64 s[2:3], s[48:49], s[50:51]
	s_or_b64 s[2:3], s[2:3], s[46:47]
	s_or_b64 s[2:3], s[2:3], s[42:43]
	s_cmp_eq_u64 s[2:3], 0
	s_cbranch_scc1 .LBB0_840
	ds_read_b128 v[182:185], v246 offset:16384
	ds_read_b128 v[178:181], v246 offset:18432
	ds_read_b128 v[186:189], v247 offset:16384
	ds_read_b128 v[174:177], v247 offset:18432
	ds_read_b128 v[158:161], v244 offset:20480
	ds_read_b128 v[162:165], v244 offset:21504
	ds_read_b128 v[166:169], v244 offset:22528
	ds_read_b128 v[170:173], v244 offset:23552
	s_add_i32 s2, s28, 0xffffff3f
	s_cmp_le_i32 s2, s26
	s_cselect_b64 s[2:3], -1, 0
	v_cndmask_b32_e64 v0, 0, 1, s[2:3]
	s_cmp_eq_u64 s[50:51], 0
	v_cmp_ne_u32_e64 s[44:45], 1, v0
	s_cbranch_scc1 .LBB0_822
	s_waitcnt lgkmcnt(7)
	v_mfma_f32_16x16x32_bf16 v[0:3], v[182:185], v[104:107], 0
	s_and_b64 vcc, exec, s[44:45]
	s_mov_b64 s[40:41], -1
	s_waitcnt lgkmcnt(6)
	v_mfma_f32_16x16x32_bf16 v[4:7], v[178:181], v[104:107], 0
	s_waitcnt lgkmcnt(5)
	v_mfma_f32_16x16x32_bf16 v[0:3], v[186:189], v[108:111], v[0:3]
	s_waitcnt lgkmcnt(4)
	v_mfma_f32_16x16x32_bf16 v[4:7], v[174:177], v[108:111], v[4:7]
	s_nop 5
	v_exp_f32_e32 v0, v0
	v_exp_f32_e32 v1, v1
	v_exp_f32_e32 v2, v2
	v_exp_f32_e32 v3, v3
	v_exp_f32_e32 v4, v4
	v_exp_f32_e32 v5, v5
	v_exp_f32_e32 v6, v6
	v_exp_f32_e32 v7, v7
	s_cbranch_vccnz .LBB0_819
	s_mov_b64 s[40:41], 0

.LBB0_840:
	s_mov_b64 s[50:51], s[86:87]
	s_mov_b64 s[48:49], s[88:89]
	s_mov_b64 s[46:47], s[90:91]
	s_mov_b64 s[42:43], s[92:93]
	s_or_b64 s[2:3], s[48:49], s[50:51]
	s_or_b64 s[2:3], s[2:3], s[46:47]
	s_or_b64 s[2:3], s[2:3], s[42:43]
	s_cmp_eq_u64 s[2:3], 0
	s_cbranch_scc1 .LBB0_754
	ds_read_b128 v[182:185], v246 offset:24576
	ds_read_b128 v[178:181], v246 offset:26624
	ds_read_b128 v[186:189], v247 offset:24576
	ds_read_b128 v[174:177], v247 offset:26624
	ds_read_b128 v[158:161], v244 offset:28672
	ds_read_b128 v[162:165], v244 offset:29696
	ds_read_b128 v[166:169], v244 offset:30720
	ds_read_b128 v[170:173], v244 offset:31744
	s_add_i32 s2, s28, 0xffffff5f
	s_cmp_le_i32 s2, s26
	s_cselect_b64 s[2:3], -1, 0
	v_cndmask_b32_e64 v0, 0, 1, s[2:3]
	s_cmp_eq_u64 s[50:51], 0
	v_cmp_ne_u32_e64 s[44:45], 1, v0
	s_cbranch_scc1 .LBB0_847
	s_waitcnt lgkmcnt(7)
	v_mfma_f32_16x16x32_bf16 v[0:3], v[182:185], v[104:107], 0
	s_and_b64 vcc, exec, s[44:45]
	s_mov_b64 s[40:41], -1
	s_waitcnt lgkmcnt(6)
	v_mfma_f32_16x16x32_bf16 v[4:7], v[178:181], v[104:107], 0
	s_waitcnt lgkmcnt(5)
	v_mfma_f32_16x16x32_bf16 v[0:3], v[186:189], v[108:111], v[0:3]
	s_waitcnt lgkmcnt(4)
	v_mfma_f32_16x16x32_bf16 v[4:7], v[174:177], v[108:111], v[4:7]
	s_nop 5
	v_exp_f32_e32 v0, v0
	v_exp_f32_e32 v1, v1
	v_exp_f32_e32 v2, v2
	v_exp_f32_e32 v3, v3
	v_exp_f32_e32 v4, v4
	v_exp_f32_e32 v5, v5
	v_exp_f32_e32 v6, v6
	v_exp_f32_e32 v7, v7
	s_cbranch_vccnz .LBB0_844
	s_mov_b64 s[40:41], 0
